# second measure of v42 (400 v_nop pacing in the w_up int8 transpose loop)
# speedup vs baseline: 1.0135x; 1.0056x over previous
; __device__ __forceinline__ void ph_transpose_q8(const TrJob job, LAS unsigned* scr, int gw, int NGW, int lane) {
;     ...
;     for (int item = gw; item < nitems; item += NGW) {
;         const int kb = item / ngrp, gq = item % ngrp, k0 = 64 * kb, r0 = 64 * gq, sb = srcbase_of(job.kind, r0);
;     ...
;           for (int i = 0; i < 4; ++i) { const int kq = 4 * i + (lane >> 4);
; #pragma unroll
;               for (int q = 0; q < 4; ++q) { const int k = k0 + 4 * kq + q; kv[i][q] = (ks && k < job.kscale_n) ? ks[k] : 1.f; } }
.Lq8u_div_done:
	s_or_b64 exec, exec, s[56:57]
	v_nop
	v_nop
	v_nop
	v_nop
	v_nop
	v_nop
	v_nop
	v_nop
	v_nop
	v_nop
	v_nop
	v_nop
	v_nop
	v_nop
	v_nop
	v_nop
	v_nop
	v_nop
	v_nop
	v_nop
	v_nop
	v_nop
	v_nop
	v_nop
	v_nop
	v_nop
	v_nop
	v_nop
	v_nop
	v_nop
	v_nop
	v_nop
	v_nop
	v_nop
	v_nop
	v_nop
	v_nop
	v_nop
	v_nop
	v_nop
	v_nop
	v_nop
	v_nop
	v_nop
	v_nop
	v_nop
	v_nop
	v_nop
	v_nop
	v_nop
	v_nop
	v_nop
	v_nop
	v_nop
	v_nop
	v_nop
	v_nop
	v_nop
	v_nop
	v_nop
	v_nop
	v_nop
	v_nop
	v_nop
	v_nop
	v_nop
	v_nop
	v_nop
	v_nop
	v_nop
	v_nop
	v_nop
	v_nop
	v_nop
	v_nop
	v_nop
	v_nop
	v_nop
	v_nop
	v_nop
	v_nop
	v_nop
	v_nop
	v_nop
	v_nop
	v_nop
	v_nop
	v_nop
	v_nop
	v_nop
	v_nop
	v_nop
	v_nop
	v_nop
	v_nop
	v_nop
	v_nop
	v_nop
	v_nop
	v_nop
	v_nop
	v_nop
	v_nop
	v_nop
	v_nop
	v_nop
	v_nop
	v_nop
	v_nop
	v_nop
	v_nop
	v_nop
	v_nop
	v_nop
	v_nop
	v_nop
	v_nop
	v_nop
	v_nop
	v_nop
	v_nop
	v_nop
	v_nop
	v_nop
	v_nop
	v_nop
	v_nop
	v_nop
	v_nop
	v_nop
	v_nop
	v_nop
	v_nop
	v_nop
	v_nop
	v_nop
	v_nop
	v_nop
	v_nop
	v_nop
	v_nop
	v_nop
	v_nop
	v_nop
	v_nop
	v_nop
	v_nop
	v_nop
	v_nop
	v_nop
	v_nop
	v_nop
	v_nop
	v_nop
	v_nop
	v_nop
	v_nop
	v_nop
	v_nop
	v_nop
	v_nop
	v_nop
	v_nop
	v_nop
	v_nop
	v_nop
	v_nop
	v_nop
	v_nop
	v_nop
	v_nop
	v_nop
	v_nop
	v_nop
	v_nop
	v_nop
	v_nop
	v_nop
	v_nop
	v_nop
	v_nop
	v_nop
	v_nop
	v_nop
	v_nop
	v_nop
	v_nop
	v_nop
	v_nop
	v_nop
	v_nop
	v_nop
	v_nop
	v_nop
	v_nop
	v_nop
	v_nop
	v_nop
	v_nop
	v_nop
	v_nop
	v_nop
	v_nop
	v_nop
	v_nop
	v_nop
	v_nop
	v_nop
	v_nop
	v_nop
	v_nop
	v_nop
	v_nop
	v_nop
	v_nop
	v_nop
	v_nop
	v_nop
	v_nop
	v_nop
	v_nop
	v_nop
	v_nop
	v_nop
	v_nop
	v_nop
	v_nop
	v_nop
	v_nop
	v_nop
	v_nop
	v_nop
	v_nop
	v_nop
	v_nop
	v_nop
	v_nop
	v_nop
	v_nop
	v_nop
	v_nop
	v_nop
	v_nop
	v_nop
	v_nop
	v_nop
	v_nop
	v_nop
	v_nop
	v_nop
	v_nop
	v_nop
	v_nop
	v_nop
	v_nop
	v_nop
	v_nop
	v_nop
	v_nop
	v_nop
	v_nop
	v_nop
	v_nop
	v_nop
	v_nop
	v_nop
	v_nop
	v_nop
	v_nop
	v_nop
	v_nop
	v_nop
	v_nop
	v_nop
	v_nop
	v_nop
	v_nop
	v_nop
	v_nop
	v_nop
	v_nop
	v_nop
	v_nop
	v_nop
	v_nop
	v_nop
	v_nop
	v_nop
	v_nop
	v_nop
	v_nop
	v_nop
	v_nop
	v_nop
	v_nop
	v_nop
	v_nop
	v_nop
	v_nop
	v_nop
	v_nop
	v_nop
	v_nop
	v_nop
	v_nop
	v_nop
	v_nop
	v_nop
	v_nop
	v_nop
	v_nop
	v_nop
	v_nop
	v_nop
	v_nop
	v_nop
	v_nop
	v_nop
	v_nop
	v_nop
	v_nop
	v_nop
	v_nop
	v_nop
	v_nop
	v_nop
	v_nop
	v_nop
	v_nop
	v_nop
	v_nop
	v_nop
	v_nop
	v_nop
	v_nop
	v_nop
	v_nop
	v_nop
	v_nop
	v_nop
	v_nop
	v_nop
	v_nop
	v_nop
	v_nop
	v_nop
	v_nop
	v_nop
	v_nop
	v_nop
	v_nop
	v_nop
	v_nop
	v_nop
	v_nop
	v_nop
	v_nop
	v_nop
	v_nop
	v_nop
	v_nop
	v_nop
	v_nop
	v_nop
	v_nop
	v_nop
	v_nop
	v_nop
	v_nop
	v_nop
	v_nop
	v_nop
	v_nop
	v_nop
	v_nop
	v_nop
	v_nop
	v_nop
	v_nop
	v_nop
	v_nop
	v_nop
	v_nop
	v_nop
	v_nop
	v_nop
	v_nop
	v_nop
	v_nop
	v_nop
	v_nop
	v_nop
	v_nop
	v_nop
	v_nop
	v_nop
	v_nop
	v_nop
	v_nop
	v_nop
	v_cmp_gt_i32_e32 vcc, s41, v76
	s_and_b64 s[10:11], s[18:19], vcc
	v_mov_b32_e32 v78, 1.0
	v_ashrrev_i32_e32 v77, 31, v76
	v_mov_b32_e32 v80, 1.0
	s_and_saveexec_b64 s[6:7], s[10:11]
	s_cbranch_execz .LBB0_878
	v_lshl_add_u64 v[108:109], v[76:77], 2, s[16:17]
	global_load_dword v80, v[108:109], off
